# v33 + FFN-in loop: A(k0,half0) stage DMAs issued one phase later (load phases carry 2/4/4/6 DMAs instead of 2/6/2/6)
# speedup vs baseline: 1.0034x; 1.0034x over previous
; #define PG8_STAGE(bufoff, gbase, voff) do { _Pragma("unroll") for (int _i = 0; _i < 2; ++_i) \
;         __builtin_amdgcn_global_load_lds((const unsigned*)((const char*)(gbase) + (voff)[_i]), (LAS unsigned*)(lds + (bufoff) + ldsw + _i * 8192), 16, 0, 0); } while (0)
; #define PG8_LDA(dst, b, h) do { _Pragma("unroll") for (int m = 0; m < 4; ++m) _Pragma("unroll") for (int k = 0; k < 2; ++k) dst[m][k] = *(const LAS bf16x8*)(lds + PG8_SA(b, h) + aoff + m * 2048 + k * 1024); } while (0)
; #define PG8_LDB(dst, b, h) do { _Pragma("unroll") for (int n = 0; n < 2; ++n) _Pragma("unroll") for (int k = 0; k < 2; ++k) dst[n][k] = *(const LAS bf16x8*)(lds + PG8_SB(b, h) + boff + n * 2048 + k * 1024); } while (0)
; #define PG8_MMA(ai, bj, At, Bt) do { __builtin_amdgcn_s_setprio(1); _Pragma("unroll") for (int m = 0; m < 4; ++m) _Pragma("unroll") for (int n = 0; n < 2; ++n) _Pragma("unroll") for (int k = 0; k < 2; ++k) \
;         acc[ai][bj][m][n] = __builtin_amdgcn_mfma_f32_16x16x32_bf16(Bt[n][k], At[m][k], acc[ai][bj][m][n], 0, 0, 0); __builtin_amdgcn_s_setprio(0); } while (0)
; #define PG8_WAIT_V(n) asm volatile("s_waitcnt vmcnt(" #n ")" ::: "memory")
; #define PG8_WAIT_L(n) asm volatile("s_waitcnt lgkmcnt(" #n ")" ::: "memory")
; #define PG8_BAR __builtin_amdgcn_s_barrier()
; #define PG8_SCHED __builtin_amdgcn_sched_barrier(0)
; template <class Epi, class Sched>
; __device__ __forceinline__ void gemm_phase(LAS unsigned char* lds, const Gemm g, Sched S, const Epi& E) {
;     ...
;             PG8_LDB(B0, 0, 0); PG8_LDB(B1, 0, 1); PG8_SCHED; PG8_LDA(At, 0, 0); PG8_STAGE(PG8_SA(1, 1), a1 + hstepA, voffA);
;             PG8_WAIT_V(8); PG8_WAIT_L(0); PG8_BAR; PG8_MMA(0, 0, At, B0); PG8_MMA(0, 1, At, B1); PG8_BAR; PG8_SCHED;
;             PG8_LDA(At, 0, 1); PG8_STAGE(PG8_SB(0, 0), b2, voffB); PG8_STAGE(PG8_SB(0, 1), b2 + hstepB, voffB); PG8_STAGE(PG8_SA(0, 0), a2, voffA);
;             PG8_WAIT_V(8); PG8_WAIT_L(0); PG8_BAR; PG8_MMA(1, 0, At, B0); PG8_MMA(1, 1, At, B1); PG8_BAR; PG8_SCHED;
.LBB0_770:
	s_add_u32 s3, s10, 0xfffc0080
	s_addc_u32 s42, s11, -1
	s_add_i32 s71, 0, 0x10000
	s_cmp_eq_u32 s70, 12
	s_cselect_b32 s45, s60, s42
	s_cselect_b32 s44, s61, s3
	s_cselect_b32 s43, s62, s65
	s_cselect_b32 s42, s63, s64
	s_add_i32 s3, 0, 0x14000
	v_add_u32_e32 v142, s71, v183
	v_add_u32_e32 v158, s3, v183
	ds_read_b128 v[130:133], v142
	ds_read_b128 v[134:137], v142 offset:1024
	ds_read_b128 v[138:141], v142 offset:2048
	ds_read_b128 v[142:145], v142 offset:3072
	ds_read_b128 v[146:149], v158
	ds_read_b128 v[150:153], v158 offset:1024
	ds_read_b128 v[154:157], v158 offset:2048
	ds_read_b128 v[158:161], v158 offset:3072
	s_add_i32 m0, s9, 0xc000
	ds_read_b128 v[174:177], v194
	ds_read_b128 v[196:199], v194 offset:1024
	ds_read_b128 v[200:203], v194 offset:2048
	ds_read_b128 v[204:207], v194 offset:3072
	ds_read_b128 v[208:211], v194 offset:4096
	ds_read_b128 v[212:215], v194 offset:5120
	ds_read_b128 v[216:219], v194 offset:6144
	ds_read_b128 v[220:223], v194 offset:7168
	global_load_lds_dwordx4 v172, s[10:11]
	s_add_i32 m0, s9, 0xe000
	s_nop 0
	global_load_lds_dwordx4 v170, s[10:11]
	s_waitcnt vmcnt(8)
	s_waitcnt lgkmcnt(0)
	s_barrier
	s_setprio 1
	s_waitcnt lgkmcnt(0)
	v_mfma_f32_16x16x32_bf16 v[126:129], v[130:133], v[174:177], v[126:129]
	v_mfma_f32_16x16x32_bf16 v[118:121], v[138:141], v[174:177], v[118:121]
	v_mfma_f32_16x16x32_bf16 v[110:113], v[130:133], v[200:203], v[110:113]
	v_mfma_f32_16x16x32_bf16 v[102:105], v[138:141], v[200:203], v[102:105]
	v_mfma_f32_16x16x32_bf16 v[94:97], v[130:133], v[208:211], v[94:97]
	v_mfma_f32_16x16x32_bf16 v[86:89], v[138:141], v[208:211], v[86:89]
	v_mfma_f32_16x16x32_bf16 v[78:81], v[130:133], v[216:219], v[78:81]
	v_mfma_f32_16x16x32_bf16 v[70:73], v[138:141], v[216:219], v[70:73]
	v_mfma_f32_16x16x32_bf16 v[126:129], v[134:137], v[196:199], v[126:129]
	v_mfma_f32_16x16x32_bf16 v[118:121], v[142:145], v[196:199], v[118:121]
	v_mfma_f32_16x16x32_bf16 v[110:113], v[134:137], v[204:207], v[110:113]
	v_mfma_f32_16x16x32_bf16 v[102:105], v[142:145], v[204:207], v[102:105]
	v_mfma_f32_16x16x32_bf16 v[94:97], v[134:137], v[212:215], v[94:97]
	v_mfma_f32_16x16x32_bf16 v[86:89], v[142:145], v[212:215], v[86:89]
	v_mfma_f32_16x16x32_bf16 v[78:81], v[134:137], v[220:223], v[78:81]
	v_mfma_f32_16x16x32_bf16 v[70:73], v[142:145], v[220:223], v[70:73]
	s_setprio 0
	s_setprio 1
	v_mfma_f32_16x16x32_bf16 v[122:125], v[146:149], v[174:177], v[122:125]
	v_mfma_f32_16x16x32_bf16 v[114:117], v[154:157], v[174:177], v[114:117]
	v_mfma_f32_16x16x32_bf16 v[106:109], v[146:149], v[200:203], v[106:109]
	v_mfma_f32_16x16x32_bf16 v[98:101], v[154:157], v[200:203], v[98:101]
	v_mfma_f32_16x16x32_bf16 v[90:93], v[146:149], v[208:211], v[90:93]
	v_mfma_f32_16x16x32_bf16 v[82:85], v[154:157], v[208:211], v[82:85]
	v_mfma_f32_16x16x32_bf16 v[74:77], v[146:149], v[216:219], v[74:77]
	v_mfma_f32_16x16x32_bf16 v[66:69], v[154:157], v[216:219], v[66:69]
	v_mfma_f32_16x16x32_bf16 v[122:125], v[150:153], v[196:199], v[122:125]
	v_mfma_f32_16x16x32_bf16 v[114:117], v[158:161], v[196:199], v[114:117]
	v_mfma_f32_16x16x32_bf16 v[106:109], v[150:153], v[204:207], v[106:109]
	v_mfma_f32_16x16x32_bf16 v[98:101], v[158:161], v[204:207], v[98:101]
	s_setprio 2
	s_barrier
	v_mfma_f32_16x16x32_bf16 v[90:93], v[150:153], v[212:215], v[90:93]
	v_mfma_f32_16x16x32_bf16 v[82:85], v[158:161], v[212:215], v[82:85]
	v_mfma_f32_16x16x32_bf16 v[74:77], v[150:153], v[220:223], v[74:77]
	v_mfma_f32_16x16x32_bf16 v[66:69], v[158:161], v[220:223], v[66:69]
	s_setprio 0
	s_add_i32 s71, s71, s7
	s_mov_b32 m0, s71
	ds_read_b128 v[174:177], v194 offset:16384
	ds_read_b128 v[196:199], v194 offset:17408
	ds_read_b128 v[200:203], v194 offset:18432
	ds_read_b128 v[204:207], v194 offset:19456
	ds_read_b128 v[208:211], v194 offset:20480
	ds_read_b128 v[212:215], v194 offset:21504
	ds_read_b128 v[216:219], v194 offset:22528
	ds_read_b128 v[220:223], v194 offset:23552
	global_load_lds_dwordx4 v0, s[42:43]
	s_add_i32 m0, s71, 0x2000
	s_add_u32 s96, s42, 0x40000
	s_addc_u32 s97, s43, 0
	s_add_i32 s3, s3, s7
	global_load_lds_dwordx4 v164, s[42:43]
	s_mov_b32 m0, s3
	s_nop 0
	global_load_lds_dwordx4 v0, s[96:97]
	s_add_i32 m0, s3, 0x2000
	s_nop 0
	global_load_lds_dwordx4 v164, s[96:97]
	s_waitcnt vmcnt(6)
	s_waitcnt lgkmcnt(0)
	s_barrier
	s_setprio 1
	s_waitcnt lgkmcnt(0)
	v_mfma_f32_16x16x32_bf16 v[62:65], v[130:133], v[174:177], v[62:65]
	v_mfma_f32_16x16x32_bf16 v[54:57], v[138:141], v[174:177], v[54:57]
	v_mfma_f32_16x16x32_bf16 v[46:49], v[130:133], v[200:203], v[46:49]
	v_mfma_f32_16x16x32_bf16 v[38:41], v[138:141], v[200:203], v[38:41]
	v_mfma_f32_16x16x32_bf16 v[30:33], v[130:133], v[208:211], v[30:33]
	v_mfma_f32_16x16x32_bf16 v[22:25], v[138:141], v[208:211], v[22:25]
	v_mfma_f32_16x16x32_bf16 v[14:17], v[130:133], v[216:219], v[14:17]
	v_mfma_f32_16x16x32_bf16 v[6:9], v[138:141], v[216:219], v[6:9]
	v_mfma_f32_16x16x32_bf16 v[62:65], v[134:137], v[196:199], v[62:65]
	v_mfma_f32_16x16x32_bf16 v[54:57], v[142:145], v[196:199], v[54:57]
	v_mfma_f32_16x16x32_bf16 v[46:49], v[134:137], v[204:207], v[46:49]
	v_mfma_f32_16x16x32_bf16 v[38:41], v[142:145], v[204:207], v[38:41]
	v_mfma_f32_16x16x32_bf16 v[30:33], v[134:137], v[212:215], v[30:33]
	v_mfma_f32_16x16x32_bf16 v[22:25], v[142:145], v[212:215], v[22:25]
	v_mfma_f32_16x16x32_bf16 v[14:17], v[134:137], v[220:223], v[14:17]
	v_mfma_f32_16x16x32_bf16 v[6:9], v[142:145], v[220:223], v[6:9]
	s_setprio 0
	s_setprio 1
	v_mfma_f32_16x16x32_bf16 v[58:61], v[146:149], v[174:177], v[58:61]
	v_mfma_f32_16x16x32_bf16 v[50:53], v[154:157], v[174:177], v[50:53]
	v_mfma_f32_16x16x32_bf16 v[42:45], v[146:149], v[200:203], v[42:45]
	v_mfma_f32_16x16x32_bf16 v[34:37], v[154:157], v[200:203], v[34:37]
	v_mfma_f32_16x16x32_bf16 v[26:29], v[146:149], v[208:211], v[26:29]
	v_mfma_f32_16x16x32_bf16 v[18:21], v[154:157], v[208:211], v[18:21]
	v_mfma_f32_16x16x32_bf16 v[10:13], v[146:149], v[216:219], v[10:13]
	v_mfma_f32_16x16x32_bf16 v[2:5], v[154:157], v[216:219], v[2:5]
	v_mfma_f32_16x16x32_bf16 v[58:61], v[150:153], v[196:199], v[58:61]
	v_mfma_f32_16x16x32_bf16 v[50:53], v[158:161], v[196:199], v[50:53]
	v_mfma_f32_16x16x32_bf16 v[42:45], v[150:153], v[204:207], v[42:45]
	v_mfma_f32_16x16x32_bf16 v[34:37], v[158:161], v[204:207], v[34:37]
	s_setprio 2
	s_barrier
; #define PG8_STAGE(bufoff, gbase, voff) do { _Pragma("unroll") for (int _i = 0; _i < 2; ++_i) \
;         __builtin_amdgcn_global_load_lds((const unsigned*)((const char*)(gbase) + (voff)[_i]), (LAS unsigned*)(lds + (bufoff) + ldsw + _i * 8192), 16, 0, 0); } while (0)
; #define PG8_LDA(dst, b, h) do { _Pragma("unroll") for (int m = 0; m < 4; ++m) _Pragma("unroll") for (int k = 0; k < 2; ++k) dst[m][k] = *(const LAS bf16x8*)(lds + PG8_SA(b, h) + aoff + m * 2048 + k * 1024); } while (0)
; #define PG8_LDB(dst, b, h) do { _Pragma("unroll") for (int n = 0; n < 2; ++n) _Pragma("unroll") for (int k = 0; k < 2; ++k) dst[n][k] = *(const LAS bf16x8*)(lds + PG8_SB(b, h) + boff + n * 2048 + k * 1024); } while (0)
; #define PG8_MMA(ai, bj, At, Bt) do { __builtin_amdgcn_s_setprio(1); _Pragma("unroll") for (int m = 0; m < 4; ++m) _Pragma("unroll") for (int n = 0; n < 2; ++n) _Pragma("unroll") for (int k = 0; k < 2; ++k) \
;         acc[ai][bj][m][n] = __builtin_amdgcn_mfma_f32_16x16x32_bf16(Bt[n][k], At[m][k], acc[ai][bj][m][n], 0, 0, 0); __builtin_amdgcn_s_setprio(0); } while (0)
; #define PG8_WAIT_V(n) asm volatile("s_waitcnt vmcnt(" #n ")" ::: "memory")
; #define PG8_WAIT_L(n) asm volatile("s_waitcnt lgkmcnt(" #n ")" ::: "memory")
; #define PG8_BAR __builtin_amdgcn_s_barrier()
; #define PG8_SCHED __builtin_amdgcn_sched_barrier(0)
; template <class Epi, class Sched>
; __device__ __forceinline__ void gemm_phase(LAS unsigned char* lds, const Gemm g, Sched S, const Epi& E) {
;     ...
;             PG8_WAIT_V(8); PG8_WAIT_L(0); PG8_BAR; PG8_MMA(1, 0, At, B0); PG8_MMA(1, 1, At, B1); PG8_BAR; PG8_SCHED;
;             PG8_LDB(B0, 1, 0); PG8_LDB(B1, 1, 1); PG8_SCHED; PG8_LDA(At, 1, 0); PG8_STAGE(PG8_SA(0, 1), a2 + hstepA, voffA);
;             PG8_WAIT_V(8); PG8_WAIT_L(0); PG8_BAR; PG8_MMA(0, 0, At, B0); PG8_MMA(0, 1, At, B1); PG8_BAR; PG8_SCHED;
;             PG8_LDA(At, 1, 1); PG8_STAGE(PG8_SB(1, 0), b3, voffB); PG8_STAGE(PG8_SB(1, 1), b3 + hstepB, voffB); PG8_STAGE(PG8_SA(1, 0), a3, voffA);
	v_mfma_f32_16x16x32_bf16 v[26:29], v[150:153], v[212:215], v[26:29]
	v_mfma_f32_16x16x32_bf16 v[18:21], v[158:161], v[212:215], v[18:21]
	v_mfma_f32_16x16x32_bf16 v[10:13], v[150:153], v[220:223], v[10:13]
	v_mfma_f32_16x16x32_bf16 v[2:5], v[158:161], v[220:223], v[2:5]
	s_setprio 0
	s_mov_b32 m0, s9
	s_nop 0
	global_load_lds_dwordx4 v168, s[44:45]
	s_mov_b32 m0, s56
	s_nop 0
	global_load_lds_dwordx4 v166, s[44:45]
	s_add_i32 s3, 0, 0x18000
	s_add_i32 s71, 0, 0x1c000
	v_add_u32_e32 v142, s3, v183
	v_add_u32_e32 v158, s71, v183
	ds_read_b128 v[130:133], v142
	ds_read_b128 v[134:137], v142 offset:1024
	ds_read_b128 v[138:141], v142 offset:2048
	ds_read_b128 v[142:145], v142 offset:3072
	ds_read_b128 v[146:149], v158
	ds_read_b128 v[150:153], v158 offset:1024
	ds_read_b128 v[154:157], v158 offset:2048
	ds_read_b128 v[158:161], v158 offset:3072
	s_add_u32 s44, s44, 0x40000
	s_addc_u32 s45, s45, 0
	s_mov_b32 m0, s67
	ds_read_b128 v[174:177], v194 offset:32768
	ds_read_b128 v[196:199], v194 offset:33792
	ds_read_b128 v[200:203], v194 offset:34816
	ds_read_b128 v[204:207], v194 offset:35840
	ds_read_b128 v[208:211], v194 offset:36864
	ds_read_b128 v[212:215], v194 offset:37888
	ds_read_b128 v[216:219], v194 offset:38912
	ds_read_b128 v[220:223], v194 offset:39936
	global_load_lds_dwordx4 v168, s[44:45]
	s_mov_b32 m0, s72
	s_nop 0
	global_load_lds_dwordx4 v166, s[44:45]
	s_waitcnt vmcnt(8)
	s_waitcnt lgkmcnt(0)
	s_barrier
	s_setprio 1
	s_waitcnt lgkmcnt(0)
	v_mfma_f32_16x16x32_bf16 v[126:129], v[130:133], v[174:177], v[126:129]
	v_mfma_f32_16x16x32_bf16 v[118:121], v[138:141], v[174:177], v[118:121]
	v_mfma_f32_16x16x32_bf16 v[110:113], v[130:133], v[200:203], v[110:113]
	v_mfma_f32_16x16x32_bf16 v[102:105], v[138:141], v[200:203], v[102:105]
	v_mfma_f32_16x16x32_bf16 v[94:97], v[130:133], v[208:211], v[94:97]
	v_mfma_f32_16x16x32_bf16 v[86:89], v[138:141], v[208:211], v[86:89]
	v_mfma_f32_16x16x32_bf16 v[78:81], v[130:133], v[216:219], v[78:81]
	v_mfma_f32_16x16x32_bf16 v[70:73], v[138:141], v[216:219], v[70:73]
	v_mfma_f32_16x16x32_bf16 v[126:129], v[134:137], v[196:199], v[126:129]
	v_mfma_f32_16x16x32_bf16 v[118:121], v[142:145], v[196:199], v[118:121]
	v_mfma_f32_16x16x32_bf16 v[110:113], v[134:137], v[204:207], v[110:113]
	v_mfma_f32_16x16x32_bf16 v[102:105], v[142:145], v[204:207], v[102:105]
	v_mfma_f32_16x16x32_bf16 v[94:97], v[134:137], v[212:215], v[94:97]
	v_mfma_f32_16x16x32_bf16 v[86:89], v[142:145], v[212:215], v[86:89]
	v_mfma_f32_16x16x32_bf16 v[78:81], v[134:137], v[220:223], v[78:81]
	v_mfma_f32_16x16x32_bf16 v[70:73], v[142:145], v[220:223], v[70:73]
	s_setprio 0
	s_setprio 1
	v_mfma_f32_16x16x32_bf16 v[122:125], v[146:149], v[174:177], v[122:125]
	v_mfma_f32_16x16x32_bf16 v[114:117], v[154:157], v[174:177], v[114:117]
	v_mfma_f32_16x16x32_bf16 v[106:109], v[146:149], v[200:203], v[106:109]
	v_mfma_f32_16x16x32_bf16 v[98:101], v[154:157], v[200:203], v[98:101]
	v_mfma_f32_16x16x32_bf16 v[90:93], v[146:149], v[208:211], v[90:93]
	v_mfma_f32_16x16x32_bf16 v[82:85], v[154:157], v[208:211], v[82:85]
	v_mfma_f32_16x16x32_bf16 v[74:77], v[146:149], v[216:219], v[74:77]
	v_mfma_f32_16x16x32_bf16 v[66:69], v[154:157], v[216:219], v[66:69]
	v_mfma_f32_16x16x32_bf16 v[122:125], v[150:153], v[196:199], v[122:125]
	v_mfma_f32_16x16x32_bf16 v[114:117], v[158:161], v[196:199], v[114:117]
	v_mfma_f32_16x16x32_bf16 v[106:109], v[150:153], v[204:207], v[106:109]
	v_mfma_f32_16x16x32_bf16 v[98:101], v[158:161], v[204:207], v[98:101]
	s_setprio 2
	s_barrier
; #define PG8_STAGE(bufoff, gbase, voff) do { _Pragma("unroll") for (int _i = 0; _i < 2; ++_i) \
;         __builtin_amdgcn_global_load_lds((const unsigned*)((const char*)(gbase) + (voff)[_i]), (LAS unsigned*)(lds + (bufoff) + ldsw + _i * 8192), 16, 0, 0); } while (0)
; #define PG8_LDA(dst, b, h) do { _Pragma("unroll") for (int m = 0; m < 4; ++m) _Pragma("unroll") for (int k = 0; k < 2; ++k) dst[m][k] = *(const LAS bf16x8*)(lds + PG8_SA(b, h) + aoff + m * 2048 + k * 1024); } while (0)
; #define PG8_MMA(ai, bj, At, Bt) do { __builtin_amdgcn_s_setprio(1); _Pragma("unroll") for (int m = 0; m < 4; ++m) _Pragma("unroll") for (int n = 0; n < 2; ++n) _Pragma("unroll") for (int k = 0; k < 2; ++k) \
;         acc[ai][bj][m][n] = __builtin_amdgcn_mfma_f32_16x16x32_bf16(Bt[n][k], At[m][k], acc[ai][bj][m][n], 0, 0, 0); __builtin_amdgcn_s_setprio(0); } while (0)
; #define PG8_WAIT_V(n) asm volatile("s_waitcnt vmcnt(" #n ")" ::: "memory")
; #define PG8_WAIT_L(n) asm volatile("s_waitcnt lgkmcnt(" #n ")" ::: "memory")
; #define PG8_BAR __builtin_amdgcn_s_barrier()
; #define PG8_SCHED __builtin_amdgcn_sched_barrier(0)
; template <class Epi, class Sched>
; __device__ __forceinline__ void gemm_phase(LAS unsigned char* lds, const Gemm g, Sched S, const Epi& E) {
;     ...
;             PG8_LDA(At, 1, 1); PG8_STAGE(PG8_SB(1, 0), b3, voffB); PG8_STAGE(PG8_SB(1, 1), b3 + hstepB, voffB); PG8_STAGE(PG8_SA(1, 0), a3, voffA);
;             PG8_WAIT_V(8); PG8_WAIT_L(0); PG8_BAR; PG8_MMA(1, 0, At, B0); PG8_MMA(1, 1, At, B1); PG8_BAR; PG8_SCHED;
	v_mfma_f32_16x16x32_bf16 v[90:93], v[150:153], v[212:215], v[90:93]
	v_mfma_f32_16x16x32_bf16 v[82:85], v[158:161], v[212:215], v[82:85]
	v_mfma_f32_16x16x32_bf16 v[74:77], v[150:153], v[220:223], v[74:77]
	v_mfma_f32_16x16x32_bf16 v[66:69], v[158:161], v[220:223], v[66:69]
	s_setprio 0
	s_add_i32 s3, s3, s7
	s_add_u32 s100, s42, 0x80
	s_addc_u32 s101, s43, 0
	s_mov_b32 m0, s3
	ds_read_b128 v[174:177], v194 offset:49152
	ds_read_b128 v[196:199], v194 offset:50176
	ds_read_b128 v[200:203], v194 offset:51200
	ds_read_b128 v[204:207], v194 offset:52224
	ds_read_b128 v[208:211], v194 offset:53248
	ds_read_b128 v[212:215], v194 offset:54272
	ds_read_b128 v[216:219], v194 offset:55296
	ds_read_b128 v[220:223], v194 offset:56320
	global_load_lds_dwordx4 v0, s[100:101]
	s_add_i32 m0, s3, 0x2000
	s_add_u32 s42, s42, 0x40080
	s_addc_u32 s43, s43, 0
	s_add_u32 s96, s44, 0xfffc0080
	s_addc_u32 s97, s45, -1
	s_add_i32 s3, s71, s7
	global_load_lds_dwordx4 v164, s[100:101]
	s_mov_b32 m0, s3
	s_nop 0
	global_load_lds_dwordx4 v0, s[42:43]
	s_add_i32 m0, s3, 0x2000
	s_nop 0
	global_load_lds_dwordx4 v164, s[42:43]
	s_mov_b32 m0, s73
	s_nop 0
	global_load_lds_dwordx4 v168, s[96:97]
	s_mov_b32 m0, s76
	s_nop 0
	global_load_lds_dwordx4 v166, s[96:97]
	s_waitcnt vmcnt(8)
	s_waitcnt lgkmcnt(0)
	s_barrier
	s_setprio 1
	s_waitcnt lgkmcnt(0)
	v_mfma_f32_16x16x32_bf16 v[62:65], v[130:133], v[174:177], v[62:65]
	v_mfma_f32_16x16x32_bf16 v[54:57], v[138:141], v[174:177], v[54:57]
	v_mfma_f32_16x16x32_bf16 v[46:49], v[130:133], v[200:203], v[46:49]
	v_mfma_f32_16x16x32_bf16 v[38:41], v[138:141], v[200:203], v[38:41]
	v_mfma_f32_16x16x32_bf16 v[30:33], v[130:133], v[208:211], v[30:33]
	v_mfma_f32_16x16x32_bf16 v[22:25], v[138:141], v[208:211], v[22:25]
	v_mfma_f32_16x16x32_bf16 v[14:17], v[130:133], v[216:219], v[14:17]
	v_mfma_f32_16x16x32_bf16 v[6:9], v[138:141], v[216:219], v[6:9]
	v_mfma_f32_16x16x32_bf16 v[62:65], v[134:137], v[196:199], v[62:65]
	v_mfma_f32_16x16x32_bf16 v[54:57], v[142:145], v[196:199], v[54:57]
	v_mfma_f32_16x16x32_bf16 v[46:49], v[134:137], v[204:207], v[46:49]
	v_mfma_f32_16x16x32_bf16 v[38:41], v[142:145], v[204:207], v[38:41]
	v_mfma_f32_16x16x32_bf16 v[30:33], v[134:137], v[212:215], v[30:33]
	v_mfma_f32_16x16x32_bf16 v[22:25], v[142:145], v[212:215], v[22:25]
	v_mfma_f32_16x16x32_bf16 v[14:17], v[134:137], v[220:223], v[14:17]
	v_mfma_f32_16x16x32_bf16 v[6:9], v[142:145], v[220:223], v[6:9]
	s_setprio 0
	s_setprio 1
	v_mfma_f32_16x16x32_bf16 v[58:61], v[146:149], v[174:177], v[58:61]
	v_mfma_f32_16x16x32_bf16 v[50:53], v[154:157], v[174:177], v[50:53]
	v_mfma_f32_16x16x32_bf16 v[42:45], v[146:149], v[200:203], v[42:45]
	v_mfma_f32_16x16x32_bf16 v[34:37], v[154:157], v[200:203], v[34:37]
	v_mfma_f32_16x16x32_bf16 v[26:29], v[146:149], v[208:211], v[26:29]
	v_mfma_f32_16x16x32_bf16 v[18:21], v[154:157], v[208:211], v[18:21]
	v_mfma_f32_16x16x32_bf16 v[10:13], v[146:149], v[216:219], v[10:13]
	v_mfma_f32_16x16x32_bf16 v[2:5], v[154:157], v[216:219], v[2:5]
	v_mfma_f32_16x16x32_bf16 v[58:61], v[150:153], v[196:199], v[58:61]
	v_mfma_f32_16x16x32_bf16 v[50:53], v[158:161], v[196:199], v[50:53]
	v_mfma_f32_16x16x32_bf16 v[42:45], v[150:153], v[204:207], v[42:45]
	v_mfma_f32_16x16x32_bf16 v[34:37], v[158:161], v[204:207], v[34:37]
	s_setprio 2
	s_barrier
	v_mfma_f32_16x16x32_bf16 v[26:29], v[150:153], v[212:215], v[26:29]
	v_mfma_f32_16x16x32_bf16 v[18:21], v[158:161], v[212:215], v[18:21]
	v_mfma_f32_16x16x32_bf16 v[10:13], v[150:153], v[220:223], v[10:13]
	v_mfma_f32_16x16x32_bf16 v[2:5], v[158:161], v[220:223], v[2:5]
	s_setprio 0
	s_add_i32 s70, s70, 2
	s_add_u32 s64, s64, 0x100
	s_addc_u32 s65, s65, 0
	s_add_u32 s10, s10, 0x100
	s_addc_u32 s11, s11, 0
	s_cmp_gt_u32 s70, 13
	s_cbranch_scc0 .LBB0_770
	s_and_b64 vcc, exec, s[30:31]
	s_cbranch_vccz .LBB0_773
	s_barrier
